# half-tile tails: both halves of a tail tile assigned to workgroups of the same XCD
# speedup vs baseline: 1.0104x; 1.0104x over previous
.LBB0_249:
	s_add_i32 s71, s71, 1
	s_mul_i32 s18, s71, s15
	s_mul_hi_u32 s19, s71, s64
	s_add_i32 s19, s19, s18
	s_mul_i32 s18, s71, s64
	s_add_u32 s18, s18, s16
	s_addc_u32 s19, s19, s39
	s_mov_b32 s101, 0
	s_cmp_lg_u32 s71, 1
	s_cbranch_scc1 .Lh9_a
	s_movk_i32 s18, 0x140
	s_mov_b32 s19, 0
	s_cmp_gt_i32 s16, 0x7f
	s_cbranch_scc1 .Lh9_a
	s_bfe_u32 s101, s16, 0x10003
	s_add_i32 s101, s101, 1
	s_lshr_b32 s18, s16, 4
	s_lshl_b32 s18, s18, 3
	s_and_b32 s19, s16, 7
	s_or_b32 s18, s18, s19
	s_mov_b32 s19, 0
	s_addk_i32 s18, 0x100

.LBB0_687:
	s_add_i32 s87, s87, 1
	s_mul_i32 s1, s87, s15
	s_mul_hi_u32 s18, s87, s64
	s_add_i32 s1, s18, s1
	s_mul_i32 s18, s87, s64
	s_add_u32 s18, s18, s16
	s_addc_u32 s19, s1, s39
	s_mov_b32 s101, 0
	s_cmp_lg_u32 s87, 1
	s_cbranch_scc1 .Lh13_a
	s_movk_i32 s18, 0x140
	s_mov_b32 s19, 0
	s_cmp_gt_i32 s16, 0x7f
	s_cbranch_scc1 .Lh13_a
	s_bfe_u32 s101, s16, 0x10003
	s_add_i32 s101, s101, 1
	s_lshr_b32 s18, s16, 4
	s_lshl_b32 s18, s18, 3
	s_and_b32 s19, s16, 7
	s_or_b32 s18, s18, s19
	s_mov_b32 s19, 0
	s_addk_i32 s18, 0x100
